# P5: last K iteration peeled, first 8 XB residual pieces prefetched into free VGPRs under it (counted waits 16); LDS-transposed full-line epilogue stores
# baseline (speedup 1.0000x reference)
.LBB0_571:
	ds_read_b128 v[128:131], v160
	ds_read_b128 v[132:135], v160 offset:1024
	ds_read_b128 v[136:139], v160 offset:2048
	ds_read_b128 v[140:143], v160 offset:3072
	ds_read_b128 v[150:153], v161
	ds_read_b128 v[166:169], v161 offset:1024
	ds_read_b128 v[170:173], v161 offset:2048
	ds_read_b128 v[174:177], v161 offset:3072
	s_add_u32 s16, s4, 0x1000
	s_addc_u32 s17, s5, 0
	s_cmp_eq_u32 s79, 40
	s_cselect_b32 s22, s12, s16
	s_cselect_b32 s23, s13, s17
	s_cselect_b32 s20, s14, s77
	s_cselect_b32 s21, s15, s78
	s_add_u32 s18, s22, 0x800
	s_addc_u32 s19, s23, 0
	ds_read_b128 v[178:181], v162
	ds_read_b128 v[182:185], v162 offset:1024
	ds_read_b128 v[186:189], v162 offset:2048
	ds_read_b128 v[190:193], v162 offset:3072
	ds_read_b128 v[194:197], v162 offset:4096
	ds_read_b128 v[198:201], v162 offset:5120
	ds_read_b128 v[202:205], v162 offset:6144
	ds_read_b128 v[206:209], v162 offset:7168
	s_add_u32 s4, s4, 0xb0800
	s_addc_u32 s5, s5, 0
	s_mov_b32 m0, s50
	s_nop 0
	global_load_lds_dwordx4 v154, s[4:5]
	s_mov_b32 m0, s51
	s_nop 0
	global_load_lds_dwordx4 v156, s[4:5]
	s_waitcnt vmcnt(8)
	s_waitcnt lgkmcnt(0)
	s_barrier
	s_setprio 1
	s_waitcnt lgkmcnt(7)
	v_mfma_f32_16x16x32_bf16 v[124:127], v[128:131], v[178:181], v[124:127]
	v_mfma_f32_16x16x32_bf16 v[120:123], v[136:139], v[178:181], v[120:123]
	s_waitcnt lgkmcnt(5)
	v_mfma_f32_16x16x32_bf16 v[108:111], v[128:131], v[186:189], v[108:111]
	v_mfma_f32_16x16x32_bf16 v[104:107], v[136:139], v[186:189], v[104:107]
	s_waitcnt lgkmcnt(3)
	v_mfma_f32_16x16x32_bf16 v[92:95], v[128:131], v[194:197], v[92:95]
	v_mfma_f32_16x16x32_bf16 v[88:91], v[136:139], v[194:197], v[88:91]
	s_waitcnt lgkmcnt(1)
	v_mfma_f32_16x16x32_bf16 v[76:79], v[128:131], v[202:205], v[76:79]
	v_mfma_f32_16x16x32_bf16 v[72:75], v[136:139], v[202:205], v[72:75]
	v_mfma_f32_16x16x32_bf16 v[124:127], v[132:135], v[182:185], v[124:127]
	v_mfma_f32_16x16x32_bf16 v[120:123], v[140:143], v[182:185], v[120:123]
	v_mfma_f32_16x16x32_bf16 v[108:111], v[132:135], v[190:193], v[108:111]
	v_mfma_f32_16x16x32_bf16 v[104:107], v[140:143], v[190:193], v[104:107]
	v_mfma_f32_16x16x32_bf16 v[92:95], v[132:135], v[198:201], v[92:95]
	v_mfma_f32_16x16x32_bf16 v[88:91], v[140:143], v[198:201], v[88:91]
	s_waitcnt lgkmcnt(0)
	v_mfma_f32_16x16x32_bf16 v[76:79], v[132:135], v[206:209], v[76:79]
	v_mfma_f32_16x16x32_bf16 v[72:75], v[140:143], v[206:209], v[72:75]
	s_setprio 0
	s_setprio 1
	v_mfma_f32_16x16x32_bf16 v[116:119], v[150:153], v[178:181], v[116:119]
	v_mfma_f32_16x16x32_bf16 v[112:115], v[170:173], v[178:181], v[112:115]
	v_mfma_f32_16x16x32_bf16 v[100:103], v[150:153], v[186:189], v[100:103]
	v_mfma_f32_16x16x32_bf16 v[96:99], v[170:173], v[186:189], v[96:99]
	v_mfma_f32_16x16x32_bf16 v[84:87], v[150:153], v[194:197], v[84:87]
	v_mfma_f32_16x16x32_bf16 v[80:83], v[170:173], v[194:197], v[80:83]
	v_mfma_f32_16x16x32_bf16 v[68:71], v[150:153], v[202:205], v[68:71]
	v_mfma_f32_16x16x32_bf16 v[64:67], v[170:173], v[202:205], v[64:67]
	v_mfma_f32_16x16x32_bf16 v[116:119], v[166:169], v[182:185], v[116:119]
	v_mfma_f32_16x16x32_bf16 v[112:115], v[174:177], v[182:185], v[112:115]
	v_mfma_f32_16x16x32_bf16 v[100:103], v[166:169], v[190:193], v[100:103]
	v_mfma_f32_16x16x32_bf16 v[96:99], v[174:177], v[190:193], v[96:99]
	v_mfma_f32_16x16x32_bf16 v[84:87], v[166:169], v[198:201], v[84:87]
	v_mfma_f32_16x16x32_bf16 v[80:83], v[174:177], v[198:201], v[80:83]
	v_mfma_f32_16x16x32_bf16 v[68:71], v[166:169], v[206:209], v[68:71]
	v_mfma_f32_16x16x32_bf16 v[64:67], v[174:177], v[206:209], v[64:67]
	s_setprio 0
	s_barrier
	ds_read_b128 v[178:181], v162 offset:16384
	ds_read_b128 v[182:185], v162 offset:17408
	ds_read_b128 v[186:189], v162 offset:18432
	ds_read_b128 v[190:193], v162 offset:19456
	ds_read_b128 v[194:197], v162 offset:20480
	ds_read_b128 v[198:201], v162 offset:21504
	ds_read_b128 v[202:205], v162 offset:22528
	ds_read_b128 v[206:209], v162 offset:23552
	s_mov_b32 m0, s33
	s_nop 0
	global_load_lds_dwordx4 v155, s[20:21]
	s_mov_b32 m0, s36
	s_nop 0
	global_load_lds_dwordx4 v157, s[20:21]
	s_add_u32 s4, s20, 0xb0000
	s_addc_u32 s5, s21, 0
	s_mov_b32 m0, s37
	s_nop 0
	global_load_lds_dwordx4 v155, s[4:5]
	s_mov_b32 m0, s38
	s_nop 0
	global_load_lds_dwordx4 v157, s[4:5]
	s_mov_b32 m0, s30
	s_nop 0
	global_load_lds_dwordx4 v154, s[22:23]
	s_mov_b32 m0, s39
	s_nop 0
	global_load_lds_dwordx4 v156, s[22:23]
	s_waitcnt vmcnt(8)
	s_waitcnt lgkmcnt(0)
	s_barrier
	s_setprio 1
	s_waitcnt lgkmcnt(7)
	v_mfma_f32_16x16x32_bf16 v[60:63], v[128:131], v[178:181], v[60:63]
	v_mfma_f32_16x16x32_bf16 v[56:59], v[136:139], v[178:181], v[56:59]
	s_waitcnt lgkmcnt(5)
	v_mfma_f32_16x16x32_bf16 v[44:47], v[128:131], v[186:189], v[44:47]
	v_mfma_f32_16x16x32_bf16 v[40:43], v[136:139], v[186:189], v[40:43]
	s_waitcnt lgkmcnt(3)
	v_mfma_f32_16x16x32_bf16 v[28:31], v[128:131], v[194:197], v[28:31]
	v_mfma_f32_16x16x32_bf16 v[24:27], v[136:139], v[194:197], v[24:27]
	s_waitcnt lgkmcnt(1)
	v_mfma_f32_16x16x32_bf16 v[12:15], v[128:131], v[202:205], v[12:15]
	v_mfma_f32_16x16x32_bf16 v[8:11], v[136:139], v[202:205], v[8:11]
	v_mfma_f32_16x16x32_bf16 v[60:63], v[132:135], v[182:185], v[60:63]
	v_mfma_f32_16x16x32_bf16 v[56:59], v[140:143], v[182:185], v[56:59]
	v_mfma_f32_16x16x32_bf16 v[44:47], v[132:135], v[190:193], v[44:47]
	v_mfma_f32_16x16x32_bf16 v[40:43], v[140:143], v[190:193], v[40:43]
	v_mfma_f32_16x16x32_bf16 v[28:31], v[132:135], v[198:201], v[28:31]
	v_mfma_f32_16x16x32_bf16 v[24:27], v[140:143], v[198:201], v[24:27]
	s_waitcnt lgkmcnt(0)
	v_mfma_f32_16x16x32_bf16 v[12:15], v[132:135], v[206:209], v[12:15]
	v_mfma_f32_16x16x32_bf16 v[8:11], v[140:143], v[206:209], v[8:11]
	s_setprio 0
	s_setprio 1
	v_mfma_f32_16x16x32_bf16 v[52:55], v[150:153], v[178:181], v[52:55]
	v_mfma_f32_16x16x32_bf16 v[48:51], v[170:173], v[178:181], v[48:51]
	v_mfma_f32_16x16x32_bf16 v[36:39], v[150:153], v[186:189], v[36:39]
	v_mfma_f32_16x16x32_bf16 v[32:35], v[170:173], v[186:189], v[32:35]
	v_mfma_f32_16x16x32_bf16 v[20:23], v[150:153], v[194:197], v[20:23]
	v_mfma_f32_16x16x32_bf16 v[16:19], v[170:173], v[194:197], v[16:19]
	v_mfma_f32_16x16x32_bf16 v[4:7], v[150:153], v[202:205], v[4:7]
	v_mfma_f32_16x16x32_bf16 v[0:3], v[170:173], v[202:205], v[0:3]
	v_mfma_f32_16x16x32_bf16 v[52:55], v[166:169], v[182:185], v[52:55]
	v_mfma_f32_16x16x32_bf16 v[48:51], v[174:177], v[182:185], v[48:51]
	v_mfma_f32_16x16x32_bf16 v[36:39], v[166:169], v[190:193], v[36:39]
	v_mfma_f32_16x16x32_bf16 v[32:35], v[174:177], v[190:193], v[32:35]
	v_mfma_f32_16x16x32_bf16 v[20:23], v[166:169], v[198:201], v[20:23]
	v_mfma_f32_16x16x32_bf16 v[16:19], v[174:177], v[198:201], v[16:19]
	v_mfma_f32_16x16x32_bf16 v[4:7], v[166:169], v[206:209], v[4:7]
	v_mfma_f32_16x16x32_bf16 v[0:3], v[174:177], v[206:209], v[0:3]
	s_setprio 0
	s_barrier
	ds_read_b128 v[128:131], v163
	ds_read_b128 v[132:135], v163 offset:1024
	ds_read_b128 v[136:139], v163 offset:2048
	ds_read_b128 v[140:143], v163 offset:3072
	ds_read_b128 v[150:153], v164
	ds_read_b128 v[166:169], v164 offset:1024
	ds_read_b128 v[170:173], v164 offset:2048
	ds_read_b128 v[174:177], v164 offset:3072
	ds_read_b128 v[178:181], v162 offset:32768
	ds_read_b128 v[182:185], v162 offset:33792
	ds_read_b128 v[186:189], v162 offset:34816
	ds_read_b128 v[190:193], v162 offset:35840
	ds_read_b128 v[194:197], v162 offset:36864
	ds_read_b128 v[198:201], v162 offset:37888
	ds_read_b128 v[202:205], v162 offset:38912
	ds_read_b128 v[206:209], v162 offset:39936
	s_add_u32 s4, s22, 0xb0000
	s_addc_u32 s5, s23, 0
	s_mov_b32 m0, s40
	s_nop 0
	global_load_lds_dwordx4 v154, s[4:5]
	s_mov_b32 m0, s41
	s_nop 0
	global_load_lds_dwordx4 v156, s[4:5]
	s_waitcnt vmcnt(8)
	s_waitcnt lgkmcnt(0)
	s_barrier
	s_setprio 1
	s_waitcnt lgkmcnt(7)
	v_mfma_f32_16x16x32_bf16 v[124:127], v[128:131], v[178:181], v[124:127]
	v_mfma_f32_16x16x32_bf16 v[120:123], v[136:139], v[178:181], v[120:123]
	s_waitcnt lgkmcnt(5)
	v_mfma_f32_16x16x32_bf16 v[108:111], v[128:131], v[186:189], v[108:111]
	v_mfma_f32_16x16x32_bf16 v[104:107], v[136:139], v[186:189], v[104:107]
	s_waitcnt lgkmcnt(3)
	v_mfma_f32_16x16x32_bf16 v[92:95], v[128:131], v[194:197], v[92:95]
	v_mfma_f32_16x16x32_bf16 v[88:91], v[136:139], v[194:197], v[88:91]
	s_waitcnt lgkmcnt(1)
	v_mfma_f32_16x16x32_bf16 v[76:79], v[128:131], v[202:205], v[76:79]
	v_mfma_f32_16x16x32_bf16 v[72:75], v[136:139], v[202:205], v[72:75]
	v_mfma_f32_16x16x32_bf16 v[124:127], v[132:135], v[182:185], v[124:127]
	v_mfma_f32_16x16x32_bf16 v[120:123], v[140:143], v[182:185], v[120:123]
	v_mfma_f32_16x16x32_bf16 v[108:111], v[132:135], v[190:193], v[108:111]
	v_mfma_f32_16x16x32_bf16 v[104:107], v[140:143], v[190:193], v[104:107]
	v_mfma_f32_16x16x32_bf16 v[92:95], v[132:135], v[198:201], v[92:95]
	v_mfma_f32_16x16x32_bf16 v[88:91], v[140:143], v[198:201], v[88:91]
	s_waitcnt lgkmcnt(0)
	v_mfma_f32_16x16x32_bf16 v[76:79], v[132:135], v[206:209], v[76:79]
	v_mfma_f32_16x16x32_bf16 v[72:75], v[140:143], v[206:209], v[72:75]
	s_setprio 0
	s_setprio 1
	v_mfma_f32_16x16x32_bf16 v[116:119], v[150:153], v[178:181], v[116:119]
	v_mfma_f32_16x16x32_bf16 v[112:115], v[170:173], v[178:181], v[112:115]
	v_mfma_f32_16x16x32_bf16 v[100:103], v[150:153], v[186:189], v[100:103]
	v_mfma_f32_16x16x32_bf16 v[96:99], v[170:173], v[186:189], v[96:99]
	v_mfma_f32_16x16x32_bf16 v[84:87], v[150:153], v[194:197], v[84:87]
	v_mfma_f32_16x16x32_bf16 v[80:83], v[170:173], v[194:197], v[80:83]
	v_mfma_f32_16x16x32_bf16 v[68:71], v[150:153], v[202:205], v[68:71]
	v_mfma_f32_16x16x32_bf16 v[64:67], v[170:173], v[202:205], v[64:67]
	v_mfma_f32_16x16x32_bf16 v[116:119], v[166:169], v[182:185], v[116:119]
	v_mfma_f32_16x16x32_bf16 v[112:115], v[174:177], v[182:185], v[112:115]
	v_mfma_f32_16x16x32_bf16 v[100:103], v[166:169], v[190:193], v[100:103]
	v_mfma_f32_16x16x32_bf16 v[96:99], v[174:177], v[190:193], v[96:99]
	v_mfma_f32_16x16x32_bf16 v[84:87], v[166:169], v[198:201], v[84:87]
	v_mfma_f32_16x16x32_bf16 v[80:83], v[174:177], v[198:201], v[80:83]
	v_mfma_f32_16x16x32_bf16 v[68:71], v[166:169], v[206:209], v[68:71]
	v_mfma_f32_16x16x32_bf16 v[64:67], v[174:177], v[206:209], v[64:67]
	s_setprio 0
	s_barrier
	ds_read_b128 v[178:181], v162 offset:49152
	ds_read_b128 v[182:185], v162 offset:50176
	ds_read_b128 v[186:189], v162 offset:51200
	ds_read_b128 v[190:193], v162 offset:52224
	ds_read_b128 v[194:197], v162 offset:53248
	ds_read_b128 v[198:201], v162 offset:54272
	ds_read_b128 v[202:205], v162 offset:55296
	ds_read_b128 v[206:209], v162 offset:56320
	s_add_u32 s4, s20, 0x800
	s_addc_u32 s5, s21, 0
	s_mov_b32 m0, s44
	s_nop 0
	global_load_lds_dwordx4 v155, s[4:5]
	s_mov_b32 m0, s45
	s_nop 0
	global_load_lds_dwordx4 v157, s[4:5]
	s_add_u32 s4, s20, 0xb0800
	s_addc_u32 s5, s21, 0
	s_mov_b32 m0, s48
	s_nop 0
	global_load_lds_dwordx4 v155, s[4:5]
	s_mov_b32 m0, s49
	s_nop 0
	global_load_lds_dwordx4 v157, s[4:5]
	s_mov_b32 m0, s46
	s_nop 0
	global_load_lds_dwordx4 v154, s[18:19]
	s_mov_b32 m0, s47
	s_nop 0
	global_load_lds_dwordx4 v156, s[18:19]
	s_waitcnt vmcnt(8)
	s_waitcnt lgkmcnt(0)
	s_barrier
	s_setprio 1
	s_waitcnt lgkmcnt(7)
	v_mfma_f32_16x16x32_bf16 v[60:63], v[128:131], v[178:181], v[60:63]
	v_mfma_f32_16x16x32_bf16 v[56:59], v[136:139], v[178:181], v[56:59]
	s_waitcnt lgkmcnt(5)
	v_mfma_f32_16x16x32_bf16 v[44:47], v[128:131], v[186:189], v[44:47]
	v_mfma_f32_16x16x32_bf16 v[40:43], v[136:139], v[186:189], v[40:43]
	s_waitcnt lgkmcnt(3)
	v_mfma_f32_16x16x32_bf16 v[28:31], v[128:131], v[194:197], v[28:31]
	v_mfma_f32_16x16x32_bf16 v[24:27], v[136:139], v[194:197], v[24:27]
	s_waitcnt lgkmcnt(1)
	v_mfma_f32_16x16x32_bf16 v[12:15], v[128:131], v[202:205], v[12:15]
	v_mfma_f32_16x16x32_bf16 v[8:11], v[136:139], v[202:205], v[8:11]
	v_mfma_f32_16x16x32_bf16 v[60:63], v[132:135], v[182:185], v[60:63]
	v_mfma_f32_16x16x32_bf16 v[56:59], v[140:143], v[182:185], v[56:59]
	v_mfma_f32_16x16x32_bf16 v[44:47], v[132:135], v[190:193], v[44:47]
	v_mfma_f32_16x16x32_bf16 v[40:43], v[140:143], v[190:193], v[40:43]
	v_mfma_f32_16x16x32_bf16 v[28:31], v[132:135], v[198:201], v[28:31]
	v_mfma_f32_16x16x32_bf16 v[24:27], v[140:143], v[198:201], v[24:27]
	s_waitcnt lgkmcnt(0)
	v_mfma_f32_16x16x32_bf16 v[12:15], v[132:135], v[206:209], v[12:15]
	v_mfma_f32_16x16x32_bf16 v[8:11], v[140:143], v[206:209], v[8:11]
	s_setprio 0
	s_setprio 1
	v_mfma_f32_16x16x32_bf16 v[52:55], v[150:153], v[178:181], v[52:55]
	v_mfma_f32_16x16x32_bf16 v[48:51], v[170:173], v[178:181], v[48:51]
	v_mfma_f32_16x16x32_bf16 v[36:39], v[150:153], v[186:189], v[36:39]
	v_mfma_f32_16x16x32_bf16 v[32:35], v[170:173], v[186:189], v[32:35]
	v_mfma_f32_16x16x32_bf16 v[20:23], v[150:153], v[194:197], v[20:23]
	v_mfma_f32_16x16x32_bf16 v[16:19], v[170:173], v[194:197], v[16:19]
	v_mfma_f32_16x16x32_bf16 v[4:7], v[150:153], v[202:205], v[4:7]
	v_mfma_f32_16x16x32_bf16 v[0:3], v[170:173], v[202:205], v[0:3]
	v_mfma_f32_16x16x32_bf16 v[52:55], v[166:169], v[182:185], v[52:55]
	v_mfma_f32_16x16x32_bf16 v[48:51], v[174:177], v[182:185], v[48:51]
	v_mfma_f32_16x16x32_bf16 v[36:39], v[166:169], v[190:193], v[36:39]
	v_mfma_f32_16x16x32_bf16 v[32:35], v[174:177], v[190:193], v[32:35]
	v_mfma_f32_16x16x32_bf16 v[20:23], v[166:169], v[198:201], v[20:23]
	v_mfma_f32_16x16x32_bf16 v[16:19], v[174:177], v[198:201], v[16:19]
	v_mfma_f32_16x16x32_bf16 v[4:7], v[166:169], v[206:209], v[4:7]
	v_mfma_f32_16x16x32_bf16 v[0:3], v[174:177], v[206:209], v[0:3]
	s_setprio 0
	s_barrier
; #define ED_LOAD(i) do { const size_t o_ = (size_t)((((i) >> 2) * 8 + ((i) & 3)) * (D / 32)) * 512; xa[i][0] = __builtin_nontemporal_load((const u32x4*)(bp + o_)); xa[i][1] = __builtin_nontemporal_load((const u32x4*)(bp + o_ + 4 * 512)); } while (0)
;     __device__ __forceinline__ void operator()(const f32x4 (&acc)[2][2][4][2], const Unit& u, int wr, int wc, int fr, int fq) const {
;     ...
;         ED_LOAD(0); ED_LOAD(1); ED_LOAD(2); ED_LOAD(3);
	s_add_i32 s79, s79, 2
	s_add_u32 s77, s77, 0x1000
	s_addc_u32 s78, s78, 0
	s_cmp_lt_u32 s79, 40
	s_mov_b64 s[4:5], s[16:17]
	s_cbranch_scc1 .LBB0_571
	ds_read_b128 v[128:131], v160
	ds_read_b128 v[132:135], v160 offset:1024
	ds_read_b128 v[136:139], v160 offset:2048
	ds_read_b128 v[140:143], v160 offset:3072
	ds_read_b128 v[150:153], v161
	ds_read_b128 v[166:169], v161 offset:1024
	ds_read_b128 v[170:173], v161 offset:2048
	ds_read_b128 v[174:177], v161 offset:3072
	s_add_u32 s16, s4, 0x1000
	s_addc_u32 s17, s5, 0
	s_cmp_eq_u32 s79, 40
	s_cselect_b32 s22, s12, s16
	s_cselect_b32 s23, s13, s17
	s_cselect_b32 s20, s14, s77
	s_cselect_b32 s21, s15, s78
	s_add_u32 s18, s22, 0x800
	s_addc_u32 s19, s23, 0
	ds_read_b128 v[178:181], v162
	ds_read_b128 v[182:185], v162 offset:1024
	ds_read_b128 v[186:189], v162 offset:2048
	ds_read_b128 v[190:193], v162 offset:3072
	ds_read_b128 v[194:197], v162 offset:4096
	ds_read_b128 v[198:201], v162 offset:5120
	ds_read_b128 v[202:205], v162 offset:6144
	ds_read_b128 v[206:209], v162 offset:7168
	s_add_u32 s4, s4, 0xb0800
	s_addc_u32 s5, s5, 0
	s_mov_b32 m0, s50
	s_nop 0
	global_load_lds_dwordx4 v154, s[4:5]
	s_mov_b32 m0, s51
	s_nop 0
	global_load_lds_dwordx4 v156, s[4:5]
	s_waitcnt vmcnt(8)
	s_waitcnt lgkmcnt(0)
	s_barrier
	s_setprio 1
	s_waitcnt lgkmcnt(7)
	v_mfma_f32_16x16x32_bf16 v[124:127], v[128:131], v[178:181], v[124:127]
	v_mfma_f32_16x16x32_bf16 v[120:123], v[136:139], v[178:181], v[120:123]
	s_waitcnt lgkmcnt(5)
	v_mfma_f32_16x16x32_bf16 v[108:111], v[128:131], v[186:189], v[108:111]
	v_mfma_f32_16x16x32_bf16 v[104:107], v[136:139], v[186:189], v[104:107]
	s_waitcnt lgkmcnt(3)
	v_mfma_f32_16x16x32_bf16 v[92:95], v[128:131], v[194:197], v[92:95]
	v_mfma_f32_16x16x32_bf16 v[88:91], v[136:139], v[194:197], v[88:91]
	s_waitcnt lgkmcnt(1)
	v_mfma_f32_16x16x32_bf16 v[76:79], v[128:131], v[202:205], v[76:79]
	v_mfma_f32_16x16x32_bf16 v[72:75], v[136:139], v[202:205], v[72:75]
	v_mfma_f32_16x16x32_bf16 v[124:127], v[132:135], v[182:185], v[124:127]
	v_mfma_f32_16x16x32_bf16 v[120:123], v[140:143], v[182:185], v[120:123]
	v_mfma_f32_16x16x32_bf16 v[108:111], v[132:135], v[190:193], v[108:111]
	v_mfma_f32_16x16x32_bf16 v[104:107], v[140:143], v[190:193], v[104:107]
	v_mfma_f32_16x16x32_bf16 v[92:95], v[132:135], v[198:201], v[92:95]
	v_mfma_f32_16x16x32_bf16 v[88:91], v[140:143], v[198:201], v[88:91]
	s_waitcnt lgkmcnt(0)
	v_mfma_f32_16x16x32_bf16 v[76:79], v[132:135], v[206:209], v[76:79]
	v_mfma_f32_16x16x32_bf16 v[72:75], v[140:143], v[206:209], v[72:75]
	s_setprio 0
	s_setprio 1
	v_mfma_f32_16x16x32_bf16 v[116:119], v[150:153], v[178:181], v[116:119]
	v_mfma_f32_16x16x32_bf16 v[112:115], v[170:173], v[178:181], v[112:115]
	v_mfma_f32_16x16x32_bf16 v[100:103], v[150:153], v[186:189], v[100:103]
	v_mfma_f32_16x16x32_bf16 v[96:99], v[170:173], v[186:189], v[96:99]
	v_mfma_f32_16x16x32_bf16 v[84:87], v[150:153], v[194:197], v[84:87]
	v_mfma_f32_16x16x32_bf16 v[80:83], v[170:173], v[194:197], v[80:83]
	v_mfma_f32_16x16x32_bf16 v[68:71], v[150:153], v[202:205], v[68:71]
	v_mfma_f32_16x16x32_bf16 v[64:67], v[170:173], v[202:205], v[64:67]
	v_mfma_f32_16x16x32_bf16 v[116:119], v[166:169], v[182:185], v[116:119]
	v_mfma_f32_16x16x32_bf16 v[112:115], v[174:177], v[182:185], v[112:115]
	v_mfma_f32_16x16x32_bf16 v[100:103], v[166:169], v[190:193], v[100:103]
	v_mfma_f32_16x16x32_bf16 v[96:99], v[174:177], v[190:193], v[96:99]
	v_mfma_f32_16x16x32_bf16 v[84:87], v[166:169], v[198:201], v[84:87]
	v_mfma_f32_16x16x32_bf16 v[80:83], v[174:177], v[198:201], v[80:83]
	v_mfma_f32_16x16x32_bf16 v[68:71], v[166:169], v[206:209], v[68:71]
	v_mfma_f32_16x16x32_bf16 v[64:67], v[174:177], v[206:209], v[64:67]
	s_setprio 0
	s_barrier
	ds_read_b128 v[178:181], v162 offset:16384
	ds_read_b128 v[182:185], v162 offset:17408
	ds_read_b128 v[186:189], v162 offset:18432
	ds_read_b128 v[190:193], v162 offset:19456
	ds_read_b128 v[194:197], v162 offset:20480
	ds_read_b128 v[198:201], v162 offset:21504
	ds_read_b128 v[202:205], v162 offset:22528
	ds_read_b128 v[206:209], v162 offset:23552
	s_mov_b32 m0, s33
	s_nop 0
	global_load_lds_dwordx4 v155, s[20:21]
	s_mov_b32 m0, s36
	s_nop 0
	global_load_lds_dwordx4 v157, s[20:21]
	s_add_u32 s4, s20, 0xb0000
	s_addc_u32 s5, s21, 0
	s_mov_b32 m0, s37
	s_nop 0
	global_load_lds_dwordx4 v155, s[4:5]
	s_mov_b32 m0, s38
	s_nop 0
	global_load_lds_dwordx4 v157, s[4:5]
	s_mov_b32 m0, s30
	s_nop 0
	global_load_lds_dwordx4 v154, s[22:23]
	s_mov_b32 m0, s39
	s_nop 0
	global_load_lds_dwordx4 v156, s[22:23]
	s_lshl_b32 s80, s75, 19
	s_lshl_b32 s81, s42, 11
	s_add_i32 s80, s80, s81
	s_lshl_b32 s81, s76, 13
	s_add_i32 s80, s80, s81
	s_lshl_b32 s81, s43, 5
	s_add_i32 s80, s80, s81
	s_add_u32 s84, s8, s80
	s_addc_u32 s85, s9, 0
	v_lshlrev_b32_e32 v250, 4, v159
	v_lshl_or_b32 v250, v158, 6, v250
	global_load_dwordx4 v[210:213], v250, s[84:85] nt
	s_add_u32 s88, s84, 0x1000
	s_addc_u32 s89, s85, 0
	global_load_dwordx4 v[214:217], v250, s[88:89] nt
	s_add_u32 s88, s84, 0x8000
	s_addc_u32 s89, s85, 0
	global_load_dwordx4 v[218:221], v250, s[88:89] nt
	s_add_u32 s88, s84, 0x9000
	s_addc_u32 s89, s85, 0
	global_load_dwordx4 v[222:225], v250, s[88:89] nt
	s_add_u32 s88, s84, 0x10000
	s_addc_u32 s89, s85, 0
	global_load_dwordx4 v[226:229], v250, s[88:89] nt
	s_add_u32 s88, s84, 0x11000
	s_addc_u32 s89, s85, 0
	global_load_dwordx4 v[230:233], v250, s[88:89] nt
	s_add_u32 s88, s84, 0x18000
	s_addc_u32 s89, s85, 0
	global_load_dwordx4 v[234:237], v250, s[88:89] nt
	s_add_u32 s88, s84, 0x19000
	s_addc_u32 s89, s85, 0
	global_load_dwordx4 v[238:241], v250, s[88:89] nt
	s_waitcnt vmcnt(16)
	s_waitcnt lgkmcnt(0)
	s_barrier
	s_setprio 1
	s_waitcnt lgkmcnt(7)
	v_mfma_f32_16x16x32_bf16 v[60:63], v[128:131], v[178:181], v[60:63]
	v_mfma_f32_16x16x32_bf16 v[56:59], v[136:139], v[178:181], v[56:59]
	s_waitcnt lgkmcnt(5)
	v_mfma_f32_16x16x32_bf16 v[44:47], v[128:131], v[186:189], v[44:47]
	v_mfma_f32_16x16x32_bf16 v[40:43], v[136:139], v[186:189], v[40:43]
	s_waitcnt lgkmcnt(3)
	v_mfma_f32_16x16x32_bf16 v[28:31], v[128:131], v[194:197], v[28:31]
	v_mfma_f32_16x16x32_bf16 v[24:27], v[136:139], v[194:197], v[24:27]
	s_waitcnt lgkmcnt(1)
	v_mfma_f32_16x16x32_bf16 v[12:15], v[128:131], v[202:205], v[12:15]
	v_mfma_f32_16x16x32_bf16 v[8:11], v[136:139], v[202:205], v[8:11]
	v_mfma_f32_16x16x32_bf16 v[60:63], v[132:135], v[182:185], v[60:63]
	v_mfma_f32_16x16x32_bf16 v[56:59], v[140:143], v[182:185], v[56:59]
	v_mfma_f32_16x16x32_bf16 v[44:47], v[132:135], v[190:193], v[44:47]
	v_mfma_f32_16x16x32_bf16 v[40:43], v[140:143], v[190:193], v[40:43]
	v_mfma_f32_16x16x32_bf16 v[28:31], v[132:135], v[198:201], v[28:31]
	v_mfma_f32_16x16x32_bf16 v[24:27], v[140:143], v[198:201], v[24:27]
	s_waitcnt lgkmcnt(0)
	v_mfma_f32_16x16x32_bf16 v[12:15], v[132:135], v[206:209], v[12:15]
	v_mfma_f32_16x16x32_bf16 v[8:11], v[140:143], v[206:209], v[8:11]
	s_setprio 0
	s_setprio 1
	v_mfma_f32_16x16x32_bf16 v[52:55], v[150:153], v[178:181], v[52:55]
	v_mfma_f32_16x16x32_bf16 v[48:51], v[170:173], v[178:181], v[48:51]
	v_mfma_f32_16x16x32_bf16 v[36:39], v[150:153], v[186:189], v[36:39]
	v_mfma_f32_16x16x32_bf16 v[32:35], v[170:173], v[186:189], v[32:35]
	v_mfma_f32_16x16x32_bf16 v[20:23], v[150:153], v[194:197], v[20:23]
	v_mfma_f32_16x16x32_bf16 v[16:19], v[170:173], v[194:197], v[16:19]
	v_mfma_f32_16x16x32_bf16 v[4:7], v[150:153], v[202:205], v[4:7]
	v_mfma_f32_16x16x32_bf16 v[0:3], v[170:173], v[202:205], v[0:3]
	v_mfma_f32_16x16x32_bf16 v[52:55], v[166:169], v[182:185], v[52:55]
	v_mfma_f32_16x16x32_bf16 v[48:51], v[174:177], v[182:185], v[48:51]
	v_mfma_f32_16x16x32_bf16 v[36:39], v[166:169], v[190:193], v[36:39]
	v_mfma_f32_16x16x32_bf16 v[32:35], v[174:177], v[190:193], v[32:35]
	v_mfma_f32_16x16x32_bf16 v[20:23], v[166:169], v[198:201], v[20:23]
	v_mfma_f32_16x16x32_bf16 v[16:19], v[174:177], v[198:201], v[16:19]
	v_mfma_f32_16x16x32_bf16 v[4:7], v[166:169], v[206:209], v[4:7]
	v_mfma_f32_16x16x32_bf16 v[0:3], v[174:177], v[206:209], v[0:3]
	s_setprio 0
	s_barrier
	ds_read_b128 v[128:131], v163
	ds_read_b128 v[132:135], v163 offset:1024
	ds_read_b128 v[136:139], v163 offset:2048
	ds_read_b128 v[140:143], v163 offset:3072
	ds_read_b128 v[150:153], v164
	ds_read_b128 v[166:169], v164 offset:1024
	ds_read_b128 v[170:173], v164 offset:2048
	ds_read_b128 v[174:177], v164 offset:3072
	ds_read_b128 v[178:181], v162 offset:32768
	ds_read_b128 v[182:185], v162 offset:33792
	ds_read_b128 v[186:189], v162 offset:34816
	ds_read_b128 v[190:193], v162 offset:35840
	ds_read_b128 v[194:197], v162 offset:36864
	ds_read_b128 v[198:201], v162 offset:37888
	ds_read_b128 v[202:205], v162 offset:38912
	ds_read_b128 v[206:209], v162 offset:39936
	s_add_u32 s4, s22, 0xb0000
	s_addc_u32 s5, s23, 0
	s_mov_b32 m0, s40
	s_nop 0
	global_load_lds_dwordx4 v154, s[4:5]
	s_mov_b32 m0, s41
	s_nop 0
	global_load_lds_dwordx4 v156, s[4:5]
	s_waitcnt vmcnt(16)
	s_waitcnt lgkmcnt(0)
	s_barrier
	s_setprio 1
	s_waitcnt lgkmcnt(7)
	v_mfma_f32_16x16x32_bf16 v[124:127], v[128:131], v[178:181], v[124:127]
	v_mfma_f32_16x16x32_bf16 v[120:123], v[136:139], v[178:181], v[120:123]
	s_waitcnt lgkmcnt(5)
	v_mfma_f32_16x16x32_bf16 v[108:111], v[128:131], v[186:189], v[108:111]
	v_mfma_f32_16x16x32_bf16 v[104:107], v[136:139], v[186:189], v[104:107]
	s_waitcnt lgkmcnt(3)
	v_mfma_f32_16x16x32_bf16 v[92:95], v[128:131], v[194:197], v[92:95]
	v_mfma_f32_16x16x32_bf16 v[88:91], v[136:139], v[194:197], v[88:91]
	s_waitcnt lgkmcnt(1)
	v_mfma_f32_16x16x32_bf16 v[76:79], v[128:131], v[202:205], v[76:79]
	v_mfma_f32_16x16x32_bf16 v[72:75], v[136:139], v[202:205], v[72:75]
	v_mfma_f32_16x16x32_bf16 v[124:127], v[132:135], v[182:185], v[124:127]
	v_mfma_f32_16x16x32_bf16 v[120:123], v[140:143], v[182:185], v[120:123]
	v_mfma_f32_16x16x32_bf16 v[108:111], v[132:135], v[190:193], v[108:111]
	v_mfma_f32_16x16x32_bf16 v[104:107], v[140:143], v[190:193], v[104:107]
	v_mfma_f32_16x16x32_bf16 v[92:95], v[132:135], v[198:201], v[92:95]
	v_mfma_f32_16x16x32_bf16 v[88:91], v[140:143], v[198:201], v[88:91]
	s_waitcnt lgkmcnt(0)
	v_mfma_f32_16x16x32_bf16 v[76:79], v[132:135], v[206:209], v[76:79]
	v_mfma_f32_16x16x32_bf16 v[72:75], v[140:143], v[206:209], v[72:75]
	s_setprio 0
	s_setprio 1
	v_mfma_f32_16x16x32_bf16 v[116:119], v[150:153], v[178:181], v[116:119]
	v_mfma_f32_16x16x32_bf16 v[112:115], v[170:173], v[178:181], v[112:115]
	v_mfma_f32_16x16x32_bf16 v[100:103], v[150:153], v[186:189], v[100:103]
	v_mfma_f32_16x16x32_bf16 v[96:99], v[170:173], v[186:189], v[96:99]
	v_mfma_f32_16x16x32_bf16 v[84:87], v[150:153], v[194:197], v[84:87]
	v_mfma_f32_16x16x32_bf16 v[80:83], v[170:173], v[194:197], v[80:83]
	v_mfma_f32_16x16x32_bf16 v[68:71], v[150:153], v[202:205], v[68:71]
	v_mfma_f32_16x16x32_bf16 v[64:67], v[170:173], v[202:205], v[64:67]
	v_mfma_f32_16x16x32_bf16 v[116:119], v[166:169], v[182:185], v[116:119]
	v_mfma_f32_16x16x32_bf16 v[112:115], v[174:177], v[182:185], v[112:115]
	v_mfma_f32_16x16x32_bf16 v[100:103], v[166:169], v[190:193], v[100:103]
	v_mfma_f32_16x16x32_bf16 v[96:99], v[174:177], v[190:193], v[96:99]
	v_mfma_f32_16x16x32_bf16 v[84:87], v[166:169], v[198:201], v[84:87]
	v_mfma_f32_16x16x32_bf16 v[80:83], v[174:177], v[198:201], v[80:83]
	v_mfma_f32_16x16x32_bf16 v[68:71], v[166:169], v[206:209], v[68:71]
	v_mfma_f32_16x16x32_bf16 v[64:67], v[174:177], v[206:209], v[64:67]
	s_setprio 0
	s_barrier
; #define PG8_BAR __builtin_amdgcn_s_barrier()
;     __device__ __forceinline__ void operator()(const f32x4 (&acc)[2][2][4][2], const Unit& u, int wr, int wc, int fr, int fq) const {
;         const int row0 = u.pm * BM + wr * 64 + fr, col0 = u.pn * BM + wc * 32 + 8 * fq;
;         const bf16_t* __restrict__ bp = XB + tl_off(row0, col0, D);
;         const bool lodd = fr & 1; float* __restrict__ ope = out + (size_t)(row0 - (fr & 1)) * D + col0 + 4 * (fr & 1);
;         u32x4 xa[8][2];
;     ...
;         ED_LOAD(0); ED_LOAD(1); ED_LOAD(2); ED_LOAD(3);
;         asm volatile("" ::: "memory");
; #pragma unroll
;         for (int i = 0; i < 8; ++i) { const int ai = i >> 2, m = i & 3; const size_t o_ = (size_t)(ai * HALF + m * 16) * D;
; #pragma unroll
;             for (int bj = 0; bj < 2; ++bj) { const u32x4 w = xa[i][bj];
;                 const f32x4 r0 = {__builtin_bit_cast(float, w.x << 16), __builtin_bit_cast(float, w.x & 0xffff0000u), __builtin_bit_cast(float, w.y << 16), __builtin_bit_cast(float, w.y & 0xffff0000u)};
;                 const f32x4 r1 = {__builtin_bit_cast(float, w.z << 16), __builtin_bit_cast(float, w.z & 0xffff0000u), __builtin_bit_cast(float, w.w << 16), __builtin_bit_cast(float, w.w & 0xffff0000u)};
;                 const f32x4 vA = acc[ai][bj][m][0] + r0, vB = acc[ai][bj][m][1] + r1, t = lodd ? vA : vB; f32x4 g;
; #pragma unroll
;                 for (int e = 0; e < 4; ++e) { const float te = t[e]; g[e] = __builtin_bit_cast(float, __builtin_amdgcn_mov_dpp(__builtin_bit_cast(int, te), 0xB1, 0xf, 0xf, true)); }
;                 const f32x4 s1 = lodd ? g : vA, s2 = lodd ? vB : g;
;                 *(f32x4*)(ope + o_ + bj * HALF) = s1; *(f32x4*)(ope + D + o_ + bj * HALF) = s2; }
;     ...
;         int t = 0;
;         if constexpr (NT8 > 0) { const int nt8 = NT8 < nt ? NT8 : nt;
;             { PG8_ITER_FIRST(true) } t = 2;
;             _Pragma("nounroll") for (; t < nt8; t += 2) PG8_ITER(true)
;             if constexpr (NT8 < ALL8) asm volatile("s_nop 15\n\ts_nop 15" ::: "memory"); }
;         if constexpr (NT8 < ALL8) {
;             if constexpr (NT8 == 0) { { PG8_ITER_FIRST(false) } t = 2; }
;             _Pragma("nounroll") for (; t < nt; t += 2) PG8_ITER(false) }
;         if constexpr (NT8 > 0) asm volatile("s_nop 15\n\ts_nop 15\n\ts_nop 15" ::: "memory");
;         if constexpr (ALIGN_EPI) { if (wr == 0) PG8_BAR; }
	ds_read_b128 v[178:181], v162 offset:49152
	ds_read_b128 v[182:185], v162 offset:50176
	ds_read_b128 v[186:189], v162 offset:51200
	ds_read_b128 v[190:193], v162 offset:52224
	ds_read_b128 v[194:197], v162 offset:53248
	ds_read_b128 v[198:201], v162 offset:54272
	ds_read_b128 v[202:205], v162 offset:55296
	ds_read_b128 v[206:209], v162 offset:56320
	s_add_u32 s4, s20, 0x800
	s_addc_u32 s5, s21, 0
	s_mov_b32 m0, s44
	s_nop 0
	global_load_lds_dwordx4 v155, s[4:5]
	s_mov_b32 m0, s45
	s_nop 0
	global_load_lds_dwordx4 v157, s[4:5]
	s_add_u32 s4, s20, 0xb0800
	s_addc_u32 s5, s21, 0
	s_mov_b32 m0, s48
	s_nop 0
	global_load_lds_dwordx4 v155, s[4:5]
	s_mov_b32 m0, s49
	s_nop 0
	global_load_lds_dwordx4 v157, s[4:5]
	s_mov_b32 m0, s46
	s_nop 0
	global_load_lds_dwordx4 v154, s[18:19]
	s_mov_b32 m0, s47
	s_nop 0
	global_load_lds_dwordx4 v156, s[18:19]
	s_waitcnt vmcnt(16)
	s_waitcnt lgkmcnt(0)
	s_barrier
	s_setprio 1
	s_waitcnt lgkmcnt(7)
	v_mfma_f32_16x16x32_bf16 v[60:63], v[128:131], v[178:181], v[60:63]
	v_mfma_f32_16x16x32_bf16 v[56:59], v[136:139], v[178:181], v[56:59]
	s_waitcnt lgkmcnt(5)
	v_mfma_f32_16x16x32_bf16 v[44:47], v[128:131], v[186:189], v[44:47]
	v_mfma_f32_16x16x32_bf16 v[40:43], v[136:139], v[186:189], v[40:43]
	s_waitcnt lgkmcnt(3)
	v_mfma_f32_16x16x32_bf16 v[28:31], v[128:131], v[194:197], v[28:31]
	v_mfma_f32_16x16x32_bf16 v[24:27], v[136:139], v[194:197], v[24:27]
	s_waitcnt lgkmcnt(1)
	v_mfma_f32_16x16x32_bf16 v[12:15], v[128:131], v[202:205], v[12:15]
	v_mfma_f32_16x16x32_bf16 v[8:11], v[136:139], v[202:205], v[8:11]
	v_mfma_f32_16x16x32_bf16 v[60:63], v[132:135], v[182:185], v[60:63]
	v_mfma_f32_16x16x32_bf16 v[56:59], v[140:143], v[182:185], v[56:59]
	v_mfma_f32_16x16x32_bf16 v[44:47], v[132:135], v[190:193], v[44:47]
	v_mfma_f32_16x16x32_bf16 v[40:43], v[140:143], v[190:193], v[40:43]
	v_mfma_f32_16x16x32_bf16 v[28:31], v[132:135], v[198:201], v[28:31]
	v_mfma_f32_16x16x32_bf16 v[24:27], v[140:143], v[198:201], v[24:27]
	s_waitcnt lgkmcnt(0)
	v_mfma_f32_16x16x32_bf16 v[12:15], v[132:135], v[206:209], v[12:15]
	v_mfma_f32_16x16x32_bf16 v[8:11], v[140:143], v[206:209], v[8:11]
	s_setprio 0
	s_setprio 1
	v_mfma_f32_16x16x32_bf16 v[52:55], v[150:153], v[178:181], v[52:55]
	v_mfma_f32_16x16x32_bf16 v[48:51], v[170:173], v[178:181], v[48:51]
	v_mfma_f32_16x16x32_bf16 v[36:39], v[150:153], v[186:189], v[36:39]
	v_mfma_f32_16x16x32_bf16 v[32:35], v[170:173], v[186:189], v[32:35]
	v_mfma_f32_16x16x32_bf16 v[20:23], v[150:153], v[194:197], v[20:23]
	v_mfma_f32_16x16x32_bf16 v[16:19], v[170:173], v[194:197], v[16:19]
	v_mfma_f32_16x16x32_bf16 v[4:7], v[150:153], v[202:205], v[4:7]
	v_mfma_f32_16x16x32_bf16 v[0:3], v[170:173], v[202:205], v[0:3]
	v_mfma_f32_16x16x32_bf16 v[52:55], v[166:169], v[182:185], v[52:55]
	v_mfma_f32_16x16x32_bf16 v[48:51], v[174:177], v[182:185], v[48:51]
	v_mfma_f32_16x16x32_bf16 v[36:39], v[166:169], v[190:193], v[36:39]
	v_mfma_f32_16x16x32_bf16 v[32:35], v[174:177], v[190:193], v[32:35]
	v_mfma_f32_16x16x32_bf16 v[20:23], v[166:169], v[198:201], v[20:23]
	v_mfma_f32_16x16x32_bf16 v[16:19], v[174:177], v[198:201], v[16:19]
	v_mfma_f32_16x16x32_bf16 v[4:7], v[166:169], v[206:209], v[4:7]
	v_mfma_f32_16x16x32_bf16 v[0:3], v[174:177], v[206:209], v[0:3]
	s_setprio 0
	s_barrier
	s_add_i32 s79, s79, 2
	s_add_u32 s77, s77, 0x1000
	s_addc_u32 s78, s78, 0
	s_cmp_lt_u32 s79, 42
	s_mov_b64 s[4:5], s[16:17]
	s_andn2_b64 vcc, exec, s[10:11]
	s_cbranch_vccnz .LBB0_574
	s_barrier
.LBB0_574:
	s_lshl_b32 s80, s75, 20
	s_lshl_b32 s81, s42, 12
	s_add_i32 s80, s80, s81
	s_lshl_b32 s81, s76, 10
	s_add_i32 s80, s80, s81
	s_lshl_b32 s81, s43, 2
	s_add_i32 s80, s80, s81
	s_add_u32 s86, s26, s80
	s_addc_u32 s87, s27, 0
	s_lshr_b32 s80, s42, 4
	s_lshr_b32 s81, s43, 5
	s_add_i32 s80, s80, s81
	s_mulk_i32 s80, 0x900
	s_add_i32 s80, s80, 0x20000
	s_movk_i32 s81, 0x90
	v_lshl_add_u32 v252, v159, 5, s80
	v_mad_u32_u24 v252, v158, s81, v252
	v_lshrrev_b32_e32 v128, 3, v158
	v_lshl_add_u32 v128, v159, 1, v128
	v_and_b32_e32 v129, 7, v158
	v_lshlrev_b32_e32 v129, 4, v129
	v_lshl_add_u32 v251, v128, 12, v129
	v_add_u32_e32 v253, s80, v129
	v_mad_u32_u24 v253, v128, s81, v253
	s_add_u32 s88, s84, 0x40000
	s_addc_u32 s89, s85, 0
	global_load_dwordx4 v[166:169], v250, s[88:89] nt
	s_add_u32 s88, s84, 0x41000
	s_addc_u32 s89, s85, 0
	global_load_dwordx4 v[170:173], v250, s[88:89] nt
	s_add_u32 s88, s84, 0x48000
	s_addc_u32 s89, s85, 0
	global_load_dwordx4 v[174:177], v250, s[88:89] nt
	s_add_u32 s88, s84, 0x49000
	s_addc_u32 s89, s85, 0
	global_load_dwordx4 v[178:181], v250, s[88:89] nt
	s_add_u32 s88, s84, 0x50000
	s_addc_u32 s89, s85, 0
	global_load_dwordx4 v[182:185], v250, s[88:89] nt
	s_add_u32 s88, s84, 0x51000
	s_addc_u32 s89, s85, 0
	global_load_dwordx4 v[186:189], v250, s[88:89] nt
	s_add_u32 s88, s84, 0x58000
	s_addc_u32 s89, s85, 0
	global_load_dwordx4 v[190:193], v250, s[88:89] nt
	s_add_u32 s88, s84, 0x59000
	s_addc_u32 s89, s85, 0
	global_load_dwordx4 v[194:197], v250, s[88:89] nt
	s_nop 7
	s_waitcnt vmcnt(23)
	v_lshlrev_b32_e32 v128, 16, v210
	v_and_b32_e32 v129, 0xffff0000, v210
	v_lshlrev_b32_e32 v130, 16, v211
	v_and_b32_e32 v131, 0xffff0000, v211
	v_lshlrev_b32_e32 v132, 16, v212
	v_and_b32_e32 v133, 0xffff0000, v212
	v_lshlrev_b32_e32 v134, 16, v213
	v_and_b32_e32 v135, 0xffff0000, v213
	v_add_f32_e32 v124, v124, v128
	v_add_f32_e32 v125, v125, v129
	v_add_f32_e32 v126, v126, v130
	v_add_f32_e32 v127, v127, v131
	v_add_f32_e32 v120, v120, v132
	v_add_f32_e32 v121, v121, v133
	v_add_f32_e32 v122, v122, v134
	v_add_f32_e32 v123, v123, v135
	ds_write_b128 v252, v[124:127]
	ds_write_b128 v252, v[120:123] offset:16
	ds_read_b128 v[136:139], v253
	ds_read_b128 v[140:143], v253 offset:1152
	s_waitcnt vmcnt(22)
; #define ED_LOAD(i) do { const size_t o_ = (size_t)((((i) >> 2) * 8 + ((i) & 3)) * (D / 32)) * 512; xa[i][0] = __builtin_nontemporal_load((const u32x4*)(bp + o_)); xa[i][1] = __builtin_nontemporal_load((const u32x4*)(bp + o_ + 4 * 512)); } while (0)
;     __device__ __forceinline__ void operator()(const f32x4 (&acc)[2][2][4][2], const Unit& u, int wr, int wc, int fr, int fq) const {
;     ...
;         u32x4 xa[8][2];
;     ...
;         ED_LOAD(0); ED_LOAD(1); ED_LOAD(2); ED_LOAD(3);
;         asm volatile("" ::: "memory");
; #pragma unroll
;         for (int i = 0; i < 8; ++i) { const int ai = i >> 2, m = i & 3; const size_t o_ = (size_t)(ai * HALF + m * 16) * D;
; #pragma unroll
;             for (int bj = 0; bj < 2; ++bj) { const u32x4 w = xa[i][bj];
;                 const f32x4 r0 = {__builtin_bit_cast(float, w.x << 16), __builtin_bit_cast(float, w.x & 0xffff0000u), __builtin_bit_cast(float, w.y << 16), __builtin_bit_cast(float, w.y & 0xffff0000u)};
;                 const f32x4 r1 = {__builtin_bit_cast(float, w.z << 16), __builtin_bit_cast(float, w.z & 0xffff0000u), __builtin_bit_cast(float, w.w << 16), __builtin_bit_cast(float, w.w & 0xffff0000u)};
;                 const f32x4 vA = acc[ai][bj][m][0] + r0, vB = acc[ai][bj][m][1] + r1, t = lodd ? vA : vB; f32x4 g;
; #pragma unroll
;                 for (int e = 0; e < 4; ++e) { const float te = t[e]; g[e] = __builtin_bit_cast(float, __builtin_amdgcn_mov_dpp(__builtin_bit_cast(int, te), 0xB1, 0xf, 0xf, true)); }
;                 const f32x4 s1 = lodd ? g : vA, s2 = lodd ? vB : g;
;                 *(f32x4*)(ope + o_ + bj * HALF) = s1; *(f32x4*)(ope + D + o_ + bj * HALF) = s2; }
;             if (i + 4 < 8) { ED_LOAD((i + 4) & 7); }
;             asm volatile("" ::: "memory"); }
	v_lshlrev_b32_e32 v128, 16, v214
	v_and_b32_e32 v129, 0xffff0000, v214
	v_lshlrev_b32_e32 v130, 16, v215
	v_and_b32_e32 v131, 0xffff0000, v215
	v_lshlrev_b32_e32 v132, 16, v216
	v_and_b32_e32 v133, 0xffff0000, v216
	v_lshlrev_b32_e32 v134, 16, v217
	v_and_b32_e32 v135, 0xffff0000, v217
	v_add_f32_e32 v116, v116, v128
	v_add_f32_e32 v117, v117, v129
	v_add_f32_e32 v118, v118, v130
	v_add_f32_e32 v119, v119, v131
	v_add_f32_e32 v112, v112, v132
	v_add_f32_e32 v113, v113, v133
	v_add_f32_e32 v114, v114, v134
	v_add_f32_e32 v115, v115, v135
	s_waitcnt lgkmcnt(0)
	s_add_u32 s88, s86, 0x0
	s_addc_u32 s89, s87, 0
	s_add_u32 s90, s86, 0x8000
	s_addc_u32 s91, s87, 0
	global_store_dwordx4 v251, v[136:139], s[88:89]
	global_store_dwordx4 v251, v[140:143], s[90:91]
	ds_write_b128 v252, v[116:119]
	ds_write_b128 v252, v[112:115] offset:16
	ds_read_b128 v[242:245], v253
	ds_read_b128 v[246:249], v253 offset:1152
	s_waitcnt vmcnt(23)
	v_lshlrev_b32_e32 v128, 16, v218
	v_and_b32_e32 v129, 0xffff0000, v218
	v_lshlrev_b32_e32 v130, 16, v219
	v_and_b32_e32 v131, 0xffff0000, v219
	v_lshlrev_b32_e32 v132, 16, v220
	v_and_b32_e32 v133, 0xffff0000, v220
	v_lshlrev_b32_e32 v134, 16, v221
	v_and_b32_e32 v135, 0xffff0000, v221
	v_add_f32_e32 v108, v108, v128
	v_add_f32_e32 v109, v109, v129
	v_add_f32_e32 v110, v110, v130
	v_add_f32_e32 v111, v111, v131
	v_add_f32_e32 v104, v104, v132
	v_add_f32_e32 v105, v105, v133
	v_add_f32_e32 v106, v106, v134
	v_add_f32_e32 v107, v107, v135
	s_waitcnt lgkmcnt(0)
	s_add_u32 s88, s86, 0x0
	s_addc_u32 s89, s87, 0
	s_add_u32 s90, s86, 0x8000
	s_addc_u32 s91, s87, 0
	global_store_dwordx4 v251, v[242:245], s[88:89] offset:512
	global_store_dwordx4 v251, v[246:249], s[90:91] offset:512
	ds_write_b128 v252, v[108:111]
	ds_write_b128 v252, v[104:107] offset:16
	ds_read_b128 v[136:139], v253
	ds_read_b128 v[140:143], v253 offset:1152
	s_waitcnt vmcnt(24)
	v_lshlrev_b32_e32 v128, 16, v222
	v_and_b32_e32 v129, 0xffff0000, v222
	v_lshlrev_b32_e32 v130, 16, v223
	v_and_b32_e32 v131, 0xffff0000, v223
	v_lshlrev_b32_e32 v132, 16, v224
	v_and_b32_e32 v133, 0xffff0000, v224
	v_lshlrev_b32_e32 v134, 16, v225
	v_and_b32_e32 v135, 0xffff0000, v225
	v_add_f32_e32 v100, v100, v128
	v_add_f32_e32 v101, v101, v129
	v_add_f32_e32 v102, v102, v130
	v_add_f32_e32 v103, v103, v131
	v_add_f32_e32 v96, v96, v132
	v_add_f32_e32 v97, v97, v133
	v_add_f32_e32 v98, v98, v134
	v_add_f32_e32 v99, v99, v135
	s_waitcnt lgkmcnt(0)
	s_add_u32 s88, s86, 0x10000
	s_addc_u32 s89, s87, 0
	s_add_u32 s90, s86, 0x18000
	s_addc_u32 s91, s87, 0
	global_store_dwordx4 v251, v[136:139], s[88:89]
	global_store_dwordx4 v251, v[140:143], s[90:91]
	ds_write_b128 v252, v[100:103]
	ds_write_b128 v252, v[96:99] offset:16
	ds_read_b128 v[242:245], v253
	ds_read_b128 v[246:249], v253 offset:1152
	s_waitcnt vmcnt(25)
	v_lshlrev_b32_e32 v128, 16, v226
	v_and_b32_e32 v129, 0xffff0000, v226
	v_lshlrev_b32_e32 v130, 16, v227
	v_and_b32_e32 v131, 0xffff0000, v227
	v_lshlrev_b32_e32 v132, 16, v228
	v_and_b32_e32 v133, 0xffff0000, v228
	v_lshlrev_b32_e32 v134, 16, v229
	v_and_b32_e32 v135, 0xffff0000, v229
	v_add_f32_e32 v92, v92, v128
	v_add_f32_e32 v93, v93, v129
	v_add_f32_e32 v94, v94, v130
	v_add_f32_e32 v95, v95, v131
	v_add_f32_e32 v88, v88, v132
	v_add_f32_e32 v89, v89, v133
	v_add_f32_e32 v90, v90, v134
	v_add_f32_e32 v91, v91, v135
	s_waitcnt lgkmcnt(0)
	s_add_u32 s88, s86, 0x10000
	s_addc_u32 s89, s87, 0
	s_add_u32 s90, s86, 0x18000
	s_addc_u32 s91, s87, 0
	global_store_dwordx4 v251, v[242:245], s[88:89] offset:512
	global_store_dwordx4 v251, v[246:249], s[90:91] offset:512
	ds_write_b128 v252, v[92:95]
	ds_write_b128 v252, v[88:91] offset:16
	ds_read_b128 v[136:139], v253
	ds_read_b128 v[140:143], v253 offset:1152
	s_waitcnt vmcnt(26)
	v_lshlrev_b32_e32 v128, 16, v230
	v_and_b32_e32 v129, 0xffff0000, v230
	v_lshlrev_b32_e32 v130, 16, v231
	v_and_b32_e32 v131, 0xffff0000, v231
	v_lshlrev_b32_e32 v132, 16, v232
	v_and_b32_e32 v133, 0xffff0000, v232
	v_lshlrev_b32_e32 v134, 16, v233
	v_and_b32_e32 v135, 0xffff0000, v233
	v_add_f32_e32 v84, v84, v128
	v_add_f32_e32 v85, v85, v129
	v_add_f32_e32 v86, v86, v130
	v_add_f32_e32 v87, v87, v131
	v_add_f32_e32 v80, v80, v132
	v_add_f32_e32 v81, v81, v133
	v_add_f32_e32 v82, v82, v134
	v_add_f32_e32 v83, v83, v135
	s_waitcnt lgkmcnt(0)
	s_add_u32 s88, s86, 0x20000
	s_addc_u32 s89, s87, 0
	s_add_u32 s90, s86, 0x28000
	s_addc_u32 s91, s87, 0
	global_store_dwordx4 v251, v[136:139], s[88:89]
	global_store_dwordx4 v251, v[140:143], s[90:91]
	ds_write_b128 v252, v[84:87]
	ds_write_b128 v252, v[80:83] offset:16
	ds_read_b128 v[242:245], v253
	ds_read_b128 v[246:249], v253 offset:1152
	s_waitcnt vmcnt(27)
	v_lshlrev_b32_e32 v128, 16, v234
	v_and_b32_e32 v129, 0xffff0000, v234
	v_lshlrev_b32_e32 v130, 16, v235
	v_and_b32_e32 v131, 0xffff0000, v235
	v_lshlrev_b32_e32 v132, 16, v236
	v_and_b32_e32 v133, 0xffff0000, v236
	v_lshlrev_b32_e32 v134, 16, v237
	v_and_b32_e32 v135, 0xffff0000, v237
	v_add_f32_e32 v76, v76, v128
	v_add_f32_e32 v77, v77, v129
	v_add_f32_e32 v78, v78, v130
	v_add_f32_e32 v79, v79, v131
	v_add_f32_e32 v72, v72, v132
	v_add_f32_e32 v73, v73, v133
	v_add_f32_e32 v74, v74, v134
	v_add_f32_e32 v75, v75, v135
	s_waitcnt lgkmcnt(0)
	s_add_u32 s88, s86, 0x20000
	s_addc_u32 s89, s87, 0
	s_add_u32 s90, s86, 0x28000
	s_addc_u32 s91, s87, 0
	global_store_dwordx4 v251, v[242:245], s[88:89] offset:512
	global_store_dwordx4 v251, v[246:249], s[90:91] offset:512
	ds_write_b128 v252, v[76:79]
	ds_write_b128 v252, v[72:75] offset:16
	ds_read_b128 v[136:139], v253
	ds_read_b128 v[140:143], v253 offset:1152
	s_waitcnt vmcnt(28)
; #define ED_LOAD(i) do { const size_t o_ = (size_t)((((i) >> 2) * 8 + ((i) & 3)) * (D / 32)) * 512; xa[i][0] = __builtin_nontemporal_load((const u32x4*)(bp + o_)); xa[i][1] = __builtin_nontemporal_load((const u32x4*)(bp + o_ + 4 * 512)); } while (0)
;     __device__ __forceinline__ void operator()(const f32x4 (&acc)[2][2][4][2], const Unit& u, int wr, int wc, int fr, int fq) const {
;     ...
;         u32x4 xa[8][2];
;     ...
;         ED_LOAD(0); ED_LOAD(1); ED_LOAD(2); ED_LOAD(3);
;         asm volatile("" ::: "memory");
; #pragma unroll
;         for (int i = 0; i < 8; ++i) { const int ai = i >> 2, m = i & 3; const size_t o_ = (size_t)(ai * HALF + m * 16) * D;
; #pragma unroll
;             for (int bj = 0; bj < 2; ++bj) { const u32x4 w = xa[i][bj];
;                 const f32x4 r0 = {__builtin_bit_cast(float, w.x << 16), __builtin_bit_cast(float, w.x & 0xffff0000u), __builtin_bit_cast(float, w.y << 16), __builtin_bit_cast(float, w.y & 0xffff0000u)};
;                 const f32x4 r1 = {__builtin_bit_cast(float, w.z << 16), __builtin_bit_cast(float, w.z & 0xffff0000u), __builtin_bit_cast(float, w.w << 16), __builtin_bit_cast(float, w.w & 0xffff0000u)};
;                 const f32x4 vA = acc[ai][bj][m][0] + r0, vB = acc[ai][bj][m][1] + r1, t = lodd ? vA : vB; f32x4 g;
; #pragma unroll
;                 for (int e = 0; e < 4; ++e) { const float te = t[e]; g[e] = __builtin_bit_cast(float, __builtin_amdgcn_mov_dpp(__builtin_bit_cast(int, te), 0xB1, 0xf, 0xf, true)); }
;                 const f32x4 s1 = lodd ? g : vA, s2 = lodd ? vB : g;
;                 *(f32x4*)(ope + o_ + bj * HALF) = s1; *(f32x4*)(ope + D + o_ + bj * HALF) = s2; }
;             if (i + 4 < 8) { ED_LOAD((i + 4) & 7); }
;             asm volatile("" ::: "memory"); }
	v_lshlrev_b32_e32 v128, 16, v238
	v_and_b32_e32 v129, 0xffff0000, v238
	v_lshlrev_b32_e32 v130, 16, v239
	v_and_b32_e32 v131, 0xffff0000, v239
	v_lshlrev_b32_e32 v132, 16, v240
	v_and_b32_e32 v133, 0xffff0000, v240
	v_lshlrev_b32_e32 v134, 16, v241
	v_and_b32_e32 v135, 0xffff0000, v241
	v_add_f32_e32 v68, v68, v128
	v_add_f32_e32 v69, v69, v129
	v_add_f32_e32 v70, v70, v130
	v_add_f32_e32 v71, v71, v131
	v_add_f32_e32 v64, v64, v132
	v_add_f32_e32 v65, v65, v133
	v_add_f32_e32 v66, v66, v134
	v_add_f32_e32 v67, v67, v135
	s_waitcnt lgkmcnt(0)
	s_add_u32 s88, s86, 0x30000
	s_addc_u32 s89, s87, 0
	s_add_u32 s90, s86, 0x38000
	s_addc_u32 s91, s87, 0
	global_store_dwordx4 v251, v[136:139], s[88:89]
	global_store_dwordx4 v251, v[140:143], s[90:91]
	ds_write_b128 v252, v[68:71]
	ds_write_b128 v252, v[64:67] offset:16
	ds_read_b128 v[242:245], v253
	ds_read_b128 v[246:249], v253 offset:1152
	s_waitcnt vmcnt(21)
	v_lshlrev_b32_e32 v128, 16, v166
	v_and_b32_e32 v129, 0xffff0000, v166
	v_lshlrev_b32_e32 v130, 16, v167
	v_and_b32_e32 v131, 0xffff0000, v167
	v_lshlrev_b32_e32 v132, 16, v168
	v_and_b32_e32 v133, 0xffff0000, v168
	v_lshlrev_b32_e32 v134, 16, v169
	v_and_b32_e32 v135, 0xffff0000, v169
	v_add_f32_e32 v60, v60, v128
	v_add_f32_e32 v61, v61, v129
	v_add_f32_e32 v62, v62, v130
	v_add_f32_e32 v63, v63, v131
	v_add_f32_e32 v56, v56, v132
	v_add_f32_e32 v57, v57, v133
	v_add_f32_e32 v58, v58, v134
	v_add_f32_e32 v59, v59, v135
	s_waitcnt lgkmcnt(0)
	s_add_u32 s88, s86, 0x30000
	s_addc_u32 s89, s87, 0
	s_add_u32 s90, s86, 0x38000
	s_addc_u32 s91, s87, 0
	global_store_dwordx4 v251, v[242:245], s[88:89] offset:512
	global_store_dwordx4 v251, v[246:249], s[90:91] offset:512
	ds_write_b128 v252, v[60:63]
	ds_write_b128 v252, v[56:59] offset:16
	ds_read_b128 v[136:139], v253
	ds_read_b128 v[140:143], v253 offset:1152
	s_waitcnt vmcnt(22)
	v_lshlrev_b32_e32 v128, 16, v170
	v_and_b32_e32 v129, 0xffff0000, v170
	v_lshlrev_b32_e32 v130, 16, v171
	v_and_b32_e32 v131, 0xffff0000, v171
	v_lshlrev_b32_e32 v132, 16, v172
	v_and_b32_e32 v133, 0xffff0000, v172
	v_lshlrev_b32_e32 v134, 16, v173
	v_and_b32_e32 v135, 0xffff0000, v173
	v_add_f32_e32 v52, v52, v128
	v_add_f32_e32 v53, v53, v129
	v_add_f32_e32 v54, v54, v130
	v_add_f32_e32 v55, v55, v131
	v_add_f32_e32 v48, v48, v132
	v_add_f32_e32 v49, v49, v133
	v_add_f32_e32 v50, v50, v134
	v_add_f32_e32 v51, v51, v135
	s_waitcnt lgkmcnt(0)
	s_add_u32 s88, s86, 0x80000
	s_addc_u32 s89, s87, 0
	s_add_u32 s90, s86, 0x88000
	s_addc_u32 s91, s87, 0
	global_store_dwordx4 v251, v[136:139], s[88:89]
	global_store_dwordx4 v251, v[140:143], s[90:91]
	ds_write_b128 v252, v[52:55]
	ds_write_b128 v252, v[48:51] offset:16
	ds_read_b128 v[242:245], v253
	ds_read_b128 v[246:249], v253 offset:1152
	s_waitcnt vmcnt(23)
	v_lshlrev_b32_e32 v128, 16, v174
	v_and_b32_e32 v129, 0xffff0000, v174
	v_lshlrev_b32_e32 v130, 16, v175
	v_and_b32_e32 v131, 0xffff0000, v175
	v_lshlrev_b32_e32 v132, 16, v176
	v_and_b32_e32 v133, 0xffff0000, v176
	v_lshlrev_b32_e32 v134, 16, v177
	v_and_b32_e32 v135, 0xffff0000, v177
	v_add_f32_e32 v44, v44, v128
	v_add_f32_e32 v45, v45, v129
	v_add_f32_e32 v46, v46, v130
	v_add_f32_e32 v47, v47, v131
	v_add_f32_e32 v40, v40, v132
	v_add_f32_e32 v41, v41, v133
	v_add_f32_e32 v42, v42, v134
	v_add_f32_e32 v43, v43, v135
	s_waitcnt lgkmcnt(0)
	s_add_u32 s88, s86, 0x80000
	s_addc_u32 s89, s87, 0
	s_add_u32 s90, s86, 0x88000
	s_addc_u32 s91, s87, 0
	global_store_dwordx4 v251, v[242:245], s[88:89] offset:512
	global_store_dwordx4 v251, v[246:249], s[90:91] offset:512
	ds_write_b128 v252, v[44:47]
	ds_write_b128 v252, v[40:43] offset:16
	ds_read_b128 v[136:139], v253
	ds_read_b128 v[140:143], v253 offset:1152
	s_waitcnt vmcnt(24)
	v_lshlrev_b32_e32 v128, 16, v178
	v_and_b32_e32 v129, 0xffff0000, v178
	v_lshlrev_b32_e32 v130, 16, v179
	v_and_b32_e32 v131, 0xffff0000, v179
	v_lshlrev_b32_e32 v132, 16, v180
	v_and_b32_e32 v133, 0xffff0000, v180
	v_lshlrev_b32_e32 v134, 16, v181
	v_and_b32_e32 v135, 0xffff0000, v181
	v_add_f32_e32 v36, v36, v128
	v_add_f32_e32 v37, v37, v129
	v_add_f32_e32 v38, v38, v130
	v_add_f32_e32 v39, v39, v131
	v_add_f32_e32 v32, v32, v132
	v_add_f32_e32 v33, v33, v133
	v_add_f32_e32 v34, v34, v134
	v_add_f32_e32 v35, v35, v135
	s_waitcnt lgkmcnt(0)
; #define ED_LOAD(i) do { const size_t o_ = (size_t)((((i) >> 2) * 8 + ((i) & 3)) * (D / 32)) * 512; xa[i][0] = __builtin_nontemporal_load((const u32x4*)(bp + o_)); xa[i][1] = __builtin_nontemporal_load((const u32x4*)(bp + o_ + 4 * 512)); } while (0)
; #define PG8_BAR __builtin_amdgcn_s_barrier()
;     __device__ __forceinline__ void operator()(const f32x4 (&acc)[2][2][4][2], const Unit& u, int wr, int wc, int fr, int fq) const {
;     ...
;         u32x4 xa[8][2];
;     ...
;         ED_LOAD(0); ED_LOAD(1); ED_LOAD(2); ED_LOAD(3);
;         asm volatile("" ::: "memory");
; #pragma unroll
;         for (int i = 0; i < 8; ++i) { const int ai = i >> 2, m = i & 3; const size_t o_ = (size_t)(ai * HALF + m * 16) * D;
; #pragma unroll
;             for (int bj = 0; bj < 2; ++bj) { const u32x4 w = xa[i][bj];
;                 const f32x4 r0 = {__builtin_bit_cast(float, w.x << 16), __builtin_bit_cast(float, w.x & 0xffff0000u), __builtin_bit_cast(float, w.y << 16), __builtin_bit_cast(float, w.y & 0xffff0000u)};
;                 const f32x4 r1 = {__builtin_bit_cast(float, w.z << 16), __builtin_bit_cast(float, w.z & 0xffff0000u), __builtin_bit_cast(float, w.w << 16), __builtin_bit_cast(float, w.w & 0xffff0000u)};
;                 const f32x4 vA = acc[ai][bj][m][0] + r0, vB = acc[ai][bj][m][1] + r1, t = lodd ? vA : vB; f32x4 g;
; #pragma unroll
;                 for (int e = 0; e < 4; ++e) { const float te = t[e]; g[e] = __builtin_bit_cast(float, __builtin_amdgcn_mov_dpp(__builtin_bit_cast(int, te), 0xB1, 0xf, 0xf, true)); }
;                 const f32x4 s1 = lodd ? g : vA, s2 = lodd ? vB : g;
;                 *(f32x4*)(ope + o_ + bj * HALF) = s1; *(f32x4*)(ope + D + o_ + bj * HALF) = s2; }
;             if (i + 4 < 8) { ED_LOAD((i + 4) & 7); }
;             asm volatile("" ::: "memory"); }
;     ...
;         if constexpr (ALIGN_EPI) { if (wr == 0) PG8_BAR; }
;         if constexpr (!Epi::AFTER_DRAIN) { int fr_ = fr, fq_ = fq; asm volatile("" : "+v"(fr_), "+v"(fq_));
;             E(acc, cur, wr, wc, fr_, fq_); S.done(cur); }
;         if (!has_next) break;
;         cur = nxt; cA = nA; cB = nB; ++ui;
;         if constexpr (ALIGN_EPI) { if (wr == 1) PG8_BAR; }
;     }
	s_add_u32 s88, s86, 0x90000
	s_addc_u32 s89, s87, 0
	s_add_u32 s90, s86, 0x98000
	s_addc_u32 s91, s87, 0
	global_store_dwordx4 v251, v[136:139], s[88:89]
	global_store_dwordx4 v251, v[140:143], s[90:91]
	ds_write_b128 v252, v[36:39]
	ds_write_b128 v252, v[32:35] offset:16
	ds_read_b128 v[242:245], v253
	ds_read_b128 v[246:249], v253 offset:1152
	s_waitcnt vmcnt(25)
	v_lshlrev_b32_e32 v128, 16, v182
	v_and_b32_e32 v129, 0xffff0000, v182
	v_lshlrev_b32_e32 v130, 16, v183
	v_and_b32_e32 v131, 0xffff0000, v183
	v_lshlrev_b32_e32 v132, 16, v184
	v_and_b32_e32 v133, 0xffff0000, v184
	v_lshlrev_b32_e32 v134, 16, v185
	v_and_b32_e32 v135, 0xffff0000, v185
	v_add_f32_e32 v28, v28, v128
	v_add_f32_e32 v29, v29, v129
	v_add_f32_e32 v30, v30, v130
	v_add_f32_e32 v31, v31, v131
	v_add_f32_e32 v24, v24, v132
	v_add_f32_e32 v25, v25, v133
	v_add_f32_e32 v26, v26, v134
	v_add_f32_e32 v27, v27, v135
	s_waitcnt lgkmcnt(0)
	s_add_u32 s88, s86, 0x90000
	s_addc_u32 s89, s87, 0
	s_add_u32 s90, s86, 0x98000
	s_addc_u32 s91, s87, 0
	global_store_dwordx4 v251, v[242:245], s[88:89] offset:512
	global_store_dwordx4 v251, v[246:249], s[90:91] offset:512
	ds_write_b128 v252, v[28:31]
	ds_write_b128 v252, v[24:27] offset:16
	ds_read_b128 v[136:139], v253
	ds_read_b128 v[140:143], v253 offset:1152
	s_waitcnt vmcnt(26)
	v_lshlrev_b32_e32 v128, 16, v186
	v_and_b32_e32 v129, 0xffff0000, v186
	v_lshlrev_b32_e32 v130, 16, v187
	v_and_b32_e32 v131, 0xffff0000, v187
	v_lshlrev_b32_e32 v132, 16, v188
	v_and_b32_e32 v133, 0xffff0000, v188
	v_lshlrev_b32_e32 v134, 16, v189
	v_and_b32_e32 v135, 0xffff0000, v189
	v_add_f32_e32 v20, v20, v128
	v_add_f32_e32 v21, v21, v129
	v_add_f32_e32 v22, v22, v130
	v_add_f32_e32 v23, v23, v131
	v_add_f32_e32 v16, v16, v132
	v_add_f32_e32 v17, v17, v133
	v_add_f32_e32 v18, v18, v134
	v_add_f32_e32 v19, v19, v135
	s_waitcnt lgkmcnt(0)
	s_add_u32 s88, s86, 0xa0000
	s_addc_u32 s89, s87, 0
	s_add_u32 s90, s86, 0xa8000
	s_addc_u32 s91, s87, 0
	global_store_dwordx4 v251, v[136:139], s[88:89]
	global_store_dwordx4 v251, v[140:143], s[90:91]
	ds_write_b128 v252, v[20:23]
	ds_write_b128 v252, v[16:19] offset:16
	ds_read_b128 v[242:245], v253
	ds_read_b128 v[246:249], v253 offset:1152
	s_waitcnt vmcnt(27)
	v_lshlrev_b32_e32 v128, 16, v190
	v_and_b32_e32 v129, 0xffff0000, v190
	v_lshlrev_b32_e32 v130, 16, v191
	v_and_b32_e32 v131, 0xffff0000, v191
	v_lshlrev_b32_e32 v132, 16, v192
	v_and_b32_e32 v133, 0xffff0000, v192
	v_lshlrev_b32_e32 v134, 16, v193
	v_and_b32_e32 v135, 0xffff0000, v193
	v_add_f32_e32 v12, v12, v128
	v_add_f32_e32 v13, v13, v129
	v_add_f32_e32 v14, v14, v130
	v_add_f32_e32 v15, v15, v131
	v_add_f32_e32 v8, v8, v132
	v_add_f32_e32 v9, v9, v133
	v_add_f32_e32 v10, v10, v134
	v_add_f32_e32 v11, v11, v135
	s_waitcnt lgkmcnt(0)
	s_add_u32 s88, s86, 0xa0000
	s_addc_u32 s89, s87, 0
	s_add_u32 s90, s86, 0xa8000
	s_addc_u32 s91, s87, 0
	global_store_dwordx4 v251, v[242:245], s[88:89] offset:512
	global_store_dwordx4 v251, v[246:249], s[90:91] offset:512
	ds_write_b128 v252, v[12:15]
	ds_write_b128 v252, v[8:11] offset:16
	ds_read_b128 v[136:139], v253
	ds_read_b128 v[140:143], v253 offset:1152
	s_waitcnt vmcnt(28)
	v_lshlrev_b32_e32 v128, 16, v194
	v_and_b32_e32 v129, 0xffff0000, v194
	v_lshlrev_b32_e32 v130, 16, v195
	v_and_b32_e32 v131, 0xffff0000, v195
	v_lshlrev_b32_e32 v132, 16, v196
	v_and_b32_e32 v133, 0xffff0000, v196
	v_lshlrev_b32_e32 v134, 16, v197
	v_and_b32_e32 v135, 0xffff0000, v197
	v_add_f32_e32 v4, v4, v128
	v_add_f32_e32 v5, v5, v129
	v_add_f32_e32 v6, v6, v130
	v_add_f32_e32 v7, v7, v131
	v_add_f32_e32 v0, v0, v132
	v_add_f32_e32 v1, v1, v133
	v_add_f32_e32 v2, v2, v134
	v_add_f32_e32 v3, v3, v135
	s_waitcnt lgkmcnt(0)
	s_add_u32 s88, s86, 0xb0000
	s_addc_u32 s89, s87, 0
	s_add_u32 s90, s86, 0xb8000
	s_addc_u32 s91, s87, 0
	global_store_dwordx4 v251, v[136:139], s[88:89]
	global_store_dwordx4 v251, v[140:143], s[90:91]
	ds_write_b128 v252, v[4:7]
	ds_write_b128 v252, v[0:3] offset:16
	ds_read_b128 v[242:245], v253
	ds_read_b128 v[246:249], v253 offset:1152
	s_waitcnt lgkmcnt(0)
	s_add_u32 s88, s86, 0xb0000
	s_addc_u32 s89, s87, 0
	s_add_u32 s90, s86, 0xb8000
	s_addc_u32 s91, s87, 0
	global_store_dwordx4 v251, v[242:245], s[88:89] offset:512
	global_store_dwordx4 v251, v[246:249], s[90:91] offset:512
	s_and_b64 vcc, exec, s[0:1]
	s_mov_b64 s[0:1], -1
	s_cbranch_vccnz .LBB0_559
	s_andn2_b64 vcc, exec, s[6:7]
	s_cbranch_vccnz .LBB0_558
	s_barrier
	s_branch .LBB0_558

; __global__ void __launch_bounds__(NWAVES * 64, 2) fwd_megakernel(Args args) {
	.amdhsa_kernel _Z14fwd_megakernel4Args
		.amdhsa_group_segment_fixed_size 0
		.amdhsa_private_segment_fixed_size 0
		.amdhsa_kernarg_size 392
		.amdhsa_user_sgpr_count 2
		.amdhsa_user_sgpr_dispatch_ptr 0
		.amdhsa_user_sgpr_queue_ptr 0
		.amdhsa_user_sgpr_kernarg_segment_ptr 1
		.amdhsa_user_sgpr_dispatch_id 0
		.amdhsa_user_sgpr_kernarg_preload_length 0
		.amdhsa_user_sgpr_kernarg_preload_offset 0
		.amdhsa_user_sgpr_private_segment_size 0
		.amdhsa_uses_dynamic_stack 0
		.amdhsa_enable_private_segment 0
		.amdhsa_system_sgpr_workgroup_id_x 1
		.amdhsa_system_sgpr_workgroup_id_y 0
		.amdhsa_system_sgpr_workgroup_id_z 0
		.amdhsa_system_sgpr_workgroup_info 0
		.amdhsa_system_vgpr_workitem_id 0
		.amdhsa_next_free_vgpr 256
		.amdhsa_next_free_sgpr 100
		.amdhsa_accum_offset 256
		.amdhsa_reserve_vcc 1
		.amdhsa_float_round_mode_32 0
		.amdhsa_float_round_mode_16_64 0
		.amdhsa_float_denorm_mode_32 3
		.amdhsa_float_denorm_mode_16_64 3
		.amdhsa_dx10_clamp 1
		.amdhsa_ieee_mode 1
		.amdhsa_fp16_overflow 0
		.amdhsa_tg_split 0
		.amdhsa_exception_fp_ieee_invalid_op 0
		.amdhsa_exception_fp_denorm_src 0
		.amdhsa_exception_fp_ieee_div_zero 0
		.amdhsa_exception_fp_ieee_overflow 0
		.amdhsa_exception_fp_ieee_underflow 0
		.amdhsa_exception_fp_ieee_inexact 0
		.amdhsa_exception_int_div_zero 0
	.end_amdhsa_kernel

; __global__ void __launch_bounds__(NWAVES * 64, 2) fwd_megakernel(Args args) {
amdhsa.kernels:
  - .agpr_count:     0
    .args:
      - .offset:         0
        .size:           136
        .value_kind:     by_value
      - .offset:         136
        .size:           4
        .value_kind:     hidden_block_count_x
      - .offset:         140
        .size:           4
        .value_kind:     hidden_block_count_y
      - .offset:         144
        .size:           4
        .value_kind:     hidden_block_count_z
      - .offset:         148
        .size:           2
        .value_kind:     hidden_group_size_x
      - .offset:         150
        .size:           2
        .value_kind:     hidden_group_size_y
      - .offset:         152
        .size:           2
        .value_kind:     hidden_group_size_z
      - .offset:         154
        .size:           2
        .value_kind:     hidden_remainder_x
      - .offset:         156
        .size:           2
        .value_kind:     hidden_remainder_y
      - .offset:         158
        .size:           2
        .value_kind:     hidden_remainder_z
      - .offset:         176
        .size:           8
        .value_kind:     hidden_global_offset_x
      - .offset:         184
        .size:           8
        .value_kind:     hidden_global_offset_y
      - .offset:         192
        .size:           8
        .value_kind:     hidden_global_offset_z
      - .offset:         200
        .size:           2
        .value_kind:     hidden_grid_dims
      - .offset:         256
        .size:           4
        .value_kind:     hidden_dynamic_lds_size
    .group_segment_fixed_size: 0
    .kernarg_segment_align: 8
    .kernarg_segment_size: 392
    .language:       OpenCL C
    .language_version:
      - 2
      - 0
    .max_flat_workgroup_size: 512
    .name:           _Z14fwd_megakernel4Args
    .private_segment_fixed_size: 0
    .sgpr_count:     106
    .sgpr_spill_count: 4
    .symbol:         _Z14fwd_megakernel4Args.kd
    .uniform_work_group_size: 1
    .uses_dynamic_stack: false
    .vgpr_count:     256
    .vgpr_spill_count: 0
    .wavefront_size: 64
